# RG-LRU scan pass 1 computed in the gate-GEMM epilogue from the LDS-staged a/b tile (no re-read of a_arr/b_arr at the end of the attention phase)
# speedup vs baseline: 1.0015x; 1.0015x over previous
; DEV int ltid() { int t = threadIdx.x; asm volatile("" : "+v"(t)); return t; }
; __global__ void __launch_bounds__(256, 2) fwd_megakernel(Params p) {
;     ...
;                       const int t3 = ltid(), c4 = t3 & 15, r0 = t3 >> 4;
;                       const size_t gbase = ((size_t)mt * 128) * 1024 + n * 128 + hf * 64 + c4 * 4;
; #pragma unroll 4
;                       for (int ps = 0; ps < 8; ++ps) {
;                         const int r = ps * 16 + r0;
;                         *(float4*)(p.a_arr + gbase + (size_t)r * 1024) = *(const float4*)(smf + r * 68 + c4 * 4);
;                         *(float4*)(p.b_arr + gbase + (size_t)r * 1024) = *(const float4*)(smf + 8704 + r * 68 + c4 * 4);
;                       }
.LBB0_520:
	ds_read_b128 v[8:11], v6
	v_lshl_add_u64 v[12:13], v[4:5], 0, s[0:1]
	v_lshl_add_u64 v[14:15], v[2:3], 0, s[0:1]
	v_add_co_u32_e32 v16, vcc, 0x10000, v12
	s_waitcnt lgkmcnt(0)
	global_store_dwordx4 v[12:13], v[8:11], off
	ds_read_b128 v[8:11], v6 offset:34816
	v_addc_co_u32_e32 v17, vcc, 0, v13, vcc
	s_add_u32 s0, s0, 0x40000
	s_addc_u32 s1, s1, 0
	s_waitcnt lgkmcnt(0)
	global_store_dwordx4 v[14:15], v[8:11], off
	ds_read_b128 v[8:11], v6 offset:4352
	s_cmp_lg_u32 s0, 0x80000
	s_waitcnt lgkmcnt(0)
	global_store_dwordx4 v[16:17], v[8:11], off
	ds_read_b128 v[8:11], v6 offset:39168
	v_add_co_u32_e32 v16, vcc, 0x10000, v14
	s_nop 1
	v_addc_co_u32_e32 v17, vcc, 0, v15, vcc
	s_waitcnt lgkmcnt(0)
	global_store_dwordx4 v[16:17], v[8:11], off
	ds_read_b128 v[8:11], v6 offset:8704
	v_add_co_u32_e32 v16, vcc, 0x20000, v12
	s_nop 1
	v_addc_co_u32_e32 v17, vcc, 0, v13, vcc
	s_waitcnt lgkmcnt(0)
	global_store_dwordx4 v[16:17], v[8:11], off
	ds_read_b128 v[8:11], v6 offset:43520
	v_add_co_u32_e32 v16, vcc, 0x20000, v14
	s_nop 1
	v_addc_co_u32_e32 v17, vcc, 0, v15, vcc
	s_waitcnt lgkmcnt(0)
	global_store_dwordx4 v[16:17], v[8:11], off
	ds_read_b128 v[8:11], v6 offset:13056
	v_add_co_u32_e32 v12, vcc, 0x30000, v12
	s_nop 1
	v_addc_co_u32_e32 v13, vcc, 0, v13, vcc
	s_waitcnt lgkmcnt(0)
	global_store_dwordx4 v[12:13], v[8:11], off
	ds_read_b128 v[8:11], v6 offset:47872
	v_add_co_u32_e32 v12, vcc, 0x30000, v14
	v_add_u32_e32 v6, 0x4400, v6
	s_nop 0
	v_addc_co_u32_e32 v13, vcc, 0, v15, vcc
	s_waitcnt lgkmcnt(0)
	global_store_dwordx4 v[12:13], v[8:11], off
	s_cbranch_scc1 .LBB0_520
; DEV void ph_scan1(const Params& p, int item) {
;     ...
;   float A[4] = {1.f, 1.f, 1.f, 1.f}, H[4] = {0.f, 0.f, 0.f, 0.f};
; #pragma unroll 8
;   for (int t = 0; t < CHL; ++t) {
;     float4 a = *(const float4*)(p.a_arr + base + (size_t)t * 1024);
;     float4 bb = *(const float4*)(p.b_arr + base + (size_t)t * 1024);
;     A[0] *= a.x; A[1] *= a.y; A[2] *= a.z; A[3] *= a.w;
;     H[0] = a.x * H[0] + bb.x; H[1] = a.y * H[1] + bb.y; H[2] = a.z * H[2] + bb.z; H[3] = a.w * H[3] + bb.w;
;   }
;   *(float4*)(p.csA + (size_t)item * 1024 + ch) = make_float4(A[0], A[1], A[2], A[3]);
;   *(float4*)(p.csH + (size_t)item * 1024 + ch) = make_float4(H[0], H[1], H[2], H[3]);
	v_and_b32_e32 v140, 63, v0
	v_lshrrev_b32_e32 v141, 6, v0
	v_mul_u32_u24_e32 v142, 0x2200, v141
	v_lshl_add_u32 v142, v140, 2, v142
	v_add_u32_e32 v143, 0x8800, v142
	ds_read_b32 v148, v142
	ds_read_b32 v149, v142 offset:272
	ds_read_b32 v150, v142 offset:544
	ds_read_b32 v151, v142 offset:816
	ds_read_b32 v152, v142 offset:1088
	ds_read_b32 v153, v142 offset:1360
	ds_read_b32 v154, v142 offset:1632
	ds_read_b32 v155, v142 offset:1904
	ds_read_b32 v156, v142 offset:2176
	ds_read_b32 v157, v142 offset:2448
	ds_read_b32 v158, v142 offset:2720
	ds_read_b32 v159, v142 offset:2992
	ds_read_b32 v160, v142 offset:3264
	ds_read_b32 v161, v142 offset:3536
	ds_read_b32 v162, v142 offset:3808
	ds_read_b32 v163, v142 offset:4080
	ds_read_b32 v164, v142 offset:4352
	ds_read_b32 v165, v142 offset:4624
	ds_read_b32 v166, v142 offset:4896
	ds_read_b32 v167, v142 offset:5168
	ds_read_b32 v168, v142 offset:5440
	ds_read_b32 v169, v142 offset:5712
	ds_read_b32 v170, v142 offset:5984
	ds_read_b32 v171, v142 offset:6256
	ds_read_b32 v172, v142 offset:6528
	ds_read_b32 v173, v142 offset:6800
	ds_read_b32 v174, v142 offset:7072
	ds_read_b32 v175, v142 offset:7344
	ds_read_b32 v176, v142 offset:7616
	ds_read_b32 v177, v142 offset:7888
	ds_read_b32 v178, v142 offset:8160
	ds_read_b32 v179, v142 offset:8432
	ds_read_b32 v180, v143
	ds_read_b32 v181, v143 offset:272
	ds_read_b32 v182, v143 offset:544
	ds_read_b32 v183, v143 offset:816
	ds_read_b32 v184, v143 offset:1088
	ds_read_b32 v185, v143 offset:1360
	ds_read_b32 v186, v143 offset:1632
	ds_read_b32 v187, v143 offset:1904
	ds_read_b32 v188, v143 offset:2176
	ds_read_b32 v189, v143 offset:2448
	ds_read_b32 v190, v143 offset:2720
	ds_read_b32 v191, v143 offset:2992
	ds_read_b32 v192, v143 offset:3264
	ds_read_b32 v193, v143 offset:3536
	ds_read_b32 v194, v143 offset:3808
	ds_read_b32 v195, v143 offset:4080
	ds_read_b32 v196, v143 offset:4352
	ds_read_b32 v197, v143 offset:4624
	ds_read_b32 v198, v143 offset:4896
	ds_read_b32 v199, v143 offset:5168
	ds_read_b32 v200, v143 offset:5440
	ds_read_b32 v201, v143 offset:5712
	ds_read_b32 v202, v143 offset:5984
	ds_read_b32 v203, v143 offset:6256
	ds_read_b32 v204, v143 offset:6528
	ds_read_b32 v205, v143 offset:6800
	ds_read_b32 v206, v143 offset:7072
	ds_read_b32 v207, v143 offset:7344
	ds_read_b32 v208, v143 offset:7616
	ds_read_b32 v209, v143 offset:7888
	ds_read_b32 v210, v143 offset:8160
	ds_read_b32 v211, v143 offset:8432
	s_lshr_b32 s88, s51, 4
	s_lshl_b32 s88, s88, 2
	s_lshr_b32 s89, s51, 1
	s_and_b32 s89, s89, 7
	s_lshl_b32 s89, s89, 7
	s_and_b32 s93, s51, 1
	s_lshl_b32 s93, s93, 6
	s_add_u32 s89, s89, s93
	v_add_u32_e32 v144, s88, v141
	v_lshlrev_b32_e32 v144, 10, v144
	v_add3_u32 v144, v144, s89, v140
	v_lshlrev_b32_e32 v144, 2, v144
	v_readlane_b32 s96, v255, 33
	v_readlane_b32 s97, v255, 34
	v_mov_b32_e32 v145, 1.0
	v_mov_b32_e32 v146, 0
	s_waitcnt lgkmcnt(15)
	v_mul_f32_e32 v145, v145, v148
	v_fma_f32 v146, v148, v146, v180
	s_waitcnt lgkmcnt(15)
	v_mul_f32_e32 v145, v145, v149
	v_fma_f32 v146, v149, v146, v181
	s_waitcnt lgkmcnt(15)
	v_mul_f32_e32 v145, v145, v150
	v_fma_f32 v146, v150, v146, v182
	s_waitcnt lgkmcnt(15)
	v_mul_f32_e32 v145, v145, v151
	v_fma_f32 v146, v151, v146, v183
	s_waitcnt lgkmcnt(15)
	v_mul_f32_e32 v145, v145, v152
	v_fma_f32 v146, v152, v146, v184
	s_waitcnt lgkmcnt(15)
	v_mul_f32_e32 v145, v145, v153
	v_fma_f32 v146, v153, v146, v185
	s_waitcnt lgkmcnt(15)
	v_mul_f32_e32 v145, v145, v154
	v_fma_f32 v146, v154, v146, v186
	s_waitcnt lgkmcnt(15)
	v_mul_f32_e32 v145, v145, v155
	v_fma_f32 v146, v155, v146, v187
	s_waitcnt lgkmcnt(15)
	v_mul_f32_e32 v145, v145, v156
	v_fma_f32 v146, v156, v146, v188
	s_waitcnt lgkmcnt(15)
	v_mul_f32_e32 v145, v145, v157
	v_fma_f32 v146, v157, v146, v189
	s_waitcnt lgkmcnt(15)
	v_mul_f32_e32 v145, v145, v158
	v_fma_f32 v146, v158, v146, v190
	s_waitcnt lgkmcnt(15)
	v_mul_f32_e32 v145, v145, v159
	v_fma_f32 v146, v159, v146, v191
	s_waitcnt lgkmcnt(15)
	v_mul_f32_e32 v145, v145, v160
	v_fma_f32 v146, v160, v146, v192
	s_waitcnt lgkmcnt(15)
	v_mul_f32_e32 v145, v145, v161
	v_fma_f32 v146, v161, v146, v193
	s_waitcnt lgkmcnt(15)
	v_mul_f32_e32 v145, v145, v162
	v_fma_f32 v146, v162, v146, v194
	s_waitcnt lgkmcnt(15)
	v_mul_f32_e32 v145, v145, v163
	v_fma_f32 v146, v163, v146, v195
	s_waitcnt lgkmcnt(15)
	v_mul_f32_e32 v145, v145, v164
	v_fma_f32 v146, v164, v146, v196
	s_waitcnt lgkmcnt(14)
	v_mul_f32_e32 v145, v145, v165
	v_fma_f32 v146, v165, v146, v197
	s_waitcnt lgkmcnt(13)
	v_mul_f32_e32 v145, v145, v166
	v_fma_f32 v146, v166, v146, v198
	s_waitcnt lgkmcnt(12)
	v_mul_f32_e32 v145, v145, v167
	v_fma_f32 v146, v167, v146, v199
	s_waitcnt lgkmcnt(11)
	v_mul_f32_e32 v145, v145, v168
	v_fma_f32 v146, v168, v146, v200
	s_waitcnt lgkmcnt(10)
	v_mul_f32_e32 v145, v145, v169
	v_fma_f32 v146, v169, v146, v201
	s_waitcnt lgkmcnt(9)
	v_mul_f32_e32 v145, v145, v170
	v_fma_f32 v146, v170, v146, v202
	s_waitcnt lgkmcnt(8)
	v_mul_f32_e32 v145, v145, v171
	v_fma_f32 v146, v171, v146, v203
	s_waitcnt lgkmcnt(7)
	v_mul_f32_e32 v145, v145, v172
	v_fma_f32 v146, v172, v146, v204
	s_waitcnt lgkmcnt(6)
	v_mul_f32_e32 v145, v145, v173
	v_fma_f32 v146, v173, v146, v205
	s_waitcnt lgkmcnt(5)
	v_mul_f32_e32 v145, v145, v174
	v_fma_f32 v146, v174, v146, v206
	s_waitcnt lgkmcnt(4)
	v_mul_f32_e32 v145, v145, v175
	v_fma_f32 v146, v175, v146, v207
	s_waitcnt lgkmcnt(3)
	v_mul_f32_e32 v145, v145, v176
	v_fma_f32 v146, v176, v146, v208
	s_waitcnt lgkmcnt(2)
	v_mul_f32_e32 v145, v145, v177
	v_fma_f32 v146, v177, v146, v209
	s_waitcnt lgkmcnt(1)
	v_mul_f32_e32 v145, v145, v178
	v_fma_f32 v146, v178, v146, v210
	s_waitcnt lgkmcnt(0)
	v_mul_f32_e32 v145, v145, v179
	v_fma_f32 v146, v179, v146, v211
	global_store_dword v144, v145, s[96:97]
	v_readlane_b32 s96, v255, 35
	v_readlane_b32 s97, v255, 36
	s_nop 4
	global_store_dword v144, v146, s[96:97]
	s_add_i32 s51, s51, s92
	s_xor_b64 s[6:7], s[6:7], s[8:9]
	s_cmpk_gt_i32 s51, 0x7ff
	s_barrier
	s_cbranch_scc0 .LBB0_519

; DEV void attn_item(const Params& p, int item, char* smem) {
;     ...
; #pragma unroll 2
;       for (int i = 0; i < 8; ++i) {
;         const int idx = lane + i * 64, row = idx >> 4, c16 = idx & 15;
;         const u32x4 v = *(const u32x4*)(stg + row * 136 + c16 * 8);
;         *(u32x4*)(ob + (size_t)row * 1024 + c16 * 8) = v;
;       }
; DEV void ph_scan1(const Params& p, int item) {
;     ...
;   const size_t base = (size_t)(b * S_ + c * CHL) * 1024 + ch;
;   float A[4] = {1.f, 1.f, 1.f, 1.f}, H[4] = {0.f, 0.f, 0.f, 0.f};
; #pragma unroll 8
;   for (int t = 0; t < CHL; ++t) {
;     float4 a = *(const float4*)(p.a_arr + base + (size_t)t * 1024);
;     float4 bb = *(const float4*)(p.b_arr + base + (size_t)t * 1024);
;     A[0] *= a.x; A[1] *= a.y; A[2] *= a.z; A[3] *= a.w;
;     H[0] = a.x * H[0] + bb.x; H[1] = a.y * H[1] + bb.y; H[2] = a.z * H[2] + bb.z; H[3] = a.w * H[3] + bb.w;
;   }
;   *(float4*)(p.csA + (size_t)item * 1024 + ch) = make_float4(A[0], A[1], A[2], A[3]);
;   *(float4*)(p.csH + (size_t)item * 1024 + ch) = make_float4(H[0], H[1], H[2], H[3]);
; __global__ void __launch_bounds__(256, 2) fwd_megakernel(Params p) {
;     ...
;       ph_scan1(p, bid);
.LBB0_937:
	v_add_u32_e32 v40, s0, v216
	ds_read_b128 v[36:39], v40
	ds_read_b128 v[40:43], v40 offset:1088
	v_add_co_u32_e32 v44, vcc, 0x2000, v34
	s_addk_i32 s0, 0x880
	s_mov_b64 s[6:7], 0x4000
	v_addc_co_u32_e32 v45, vcc, 0, v35, vcc
	s_cmpk_eq_i32 s0, 0x2200
	s_waitcnt lgkmcnt(1)
	global_store_dwordx4 v[34:35], v[36:39], off
	s_waitcnt lgkmcnt(0)
	global_store_dwordx4 v[44:45], v[40:43], off
	v_lshl_add_u64 v[34:35], v[34:35], 0, s[6:7]
	s_cbranch_scc0 .LBB0_937
	s_mov_b32 s10, 2
	s_mov_b64 s[34:35], 0
	s_and_b64 vcc, exec, s[12:13]
	s_mov_b64 s[12:13], -1
	s_cbranch_vccz .LBB0_909
	s_branch .LBB0_942
	v_mov_b32_e32 v1, v0
	s_lshl_b32 s0, s94, 5
	s_ashr_i32 s1, s0, 31
	v_lshlrev_b32_e32 v10, 2, v1
	s_lshl_b64 s[0:1], s[0:1], 10
	v_ashrrev_i32_e32 v11, 31, v10
	v_lshl_add_u64 v[2:3], s[0:1], 0, v[10:11]
	v_readlane_b32 s0, v255, 25
	v_lshlrev_b64 v[2:3], 2, v[2:3]
	v_readlane_b32 s4, v255, 29
	v_readlane_b32 s5, v255, 30
	v_readlane_b32 s6, v255, 31
	v_readlane_b32 s7, v255, 32
	v_readlane_b32 s1, v255, 26
	v_readlane_b32 s2, v255, 27
	v_readlane_b32 s3, v255, 28
	v_lshl_add_u64 v[12:13], s[4:5], 0, v[2:3]
	v_lshl_add_u64 v[14:15], s[6:7], 0, v[2:3]
	v_mov_b32_e32 v2, 0
	v_mov_b32_e32 v6, 1.0
	v_readlane_b32 s8, v255, 33
	v_readlane_b32 s9, v255, 34
	v_readlane_b32 s10, v255, 35
	v_readlane_b32 s11, v255, 36
	s_mov_b64 s[0:1], 0
	s_movk_i32 s2, 0x2000
	s_movk_i32 s3, 0x4000
	s_movk_i32 s4, 0x6000
	s_movk_i32 s5, 0x7000
	v_mov_b32_e32 v7, v6
	v_mov_b32_e32 v8, v6
	v_mov_b32_e32 v9, v6
	v_mov_b32_e32 v3, v2
	v_mov_b32_e32 v4, v2
	v_mov_b32_e32 v5, v2
	v_readlane_b32 s12, v255, 37
	v_readlane_b32 s13, v255, 38
	v_readlane_b32 s14, v255, 39
	v_readlane_b32 s15, v255, 40
